# attention unit tails (MLA long/short, SWA): 8 dwordx2 O stores per unit -> 4 dwordx4 via v_permlane32_swap pairs; plus SWA head single wait
# speedup vs baseline: 1.0039x; 1.0039x over previous
; __device__ __forceinline__ unsigned pk2(float lo, float hi) { f32x2_t v = {lo, hi}; bf16x2_t b = __builtin_convertvector(v, bf16x2_t); return __builtin_bit_cast(unsigned, b); }
; template <bool SWA> ...
;     ...
;     int t = 0;
;     if (wv >= 4) __builtin_amdgcn_s_setprio(1);
;     for (; t < ntiles - 2; t += 2) { AT_STEP(t, sA0, sA1, sB0, sB1, true); AT_STEP(t + 1, sB0, sB1, sA0, sA1, true); }
;     AT_STEP(t, sA0, sA1, sB0, sB1, true);
;     AT_STEP(t + 1, sB0, sB1, sA0, sA1, false);
;     if (wv >= 4) __builtin_amdgcn_s_setprio(0);
;     ...
;     { auto rr = __builtin_amdgcn_permlane32_swap(__float_as_uint(lrun), __float_as_uint(lrun), false, false); lrun = __uint_as_float(rr[0]) + __uint_as_float(rr[1]); }
;     const float inv = 1.0f / lrun;
;     int tl2 = tid; asm volatile("" : "+v"(tl2));
;     bf16_t* Orow = Owave + (size_t)(tl2 & 31) * 512;
; #pragma unroll
;     for (int rq = 0; rq < 4; ++rq) {
;         u32x2 w; w.x = pk2(o0[4 * rq] * inv, o0[4 * rq + 1] * inv); w.y = pk2(o0[4 * rq + 2] * inv, o0[4 * rq + 3] * inv);
;         *(u32x2*)(Orow + 8 * rq + 4 * (tl2 & 32 ? 1 : 0)) = w;
;         w.x = pk2(o1[4 * rq] * inv, o1[4 * rq + 1] * inv); w.y = pk2(o1[4 * rq + 2] * inv, o1[4 * rq + 3] * inv);
;         *(u32x2*)(Orow + 32 + 8 * rq + 4 * (tl2 & 32 ? 1 : 0)) = w;
;     }
.LBB0_1000:
	v_add_f32_e32 v71, v67, v53
	v_mov_b32_e32 v53, v1
	v_pk_add_f32 v[46:47], v[70:71], v[52:53]
	v_add_f32_e32 v69, v65, v51
	v_pk_add_f32 v[46:47], v[46:47], v[46:47] op_sel_hi:[0,1]
	v_mov_b32_e32 v51, v47
	v_pk_add_f32 v[46:47], v[68:69], v[50:51]
	v_add_f32_e32 v67, v37, v61
	v_pk_add_f32 v[46:47], v[46:47], v[46:47] op_sel_hi:[0,1]
	v_mov_b32_e32 v65, v47
	v_pk_add_f32 v[46:47], v[66:67], v[64:65]
	v_add_f32_e32 v41, v39, v57
	v_pk_add_f32 v[46:47], v[46:47], v[46:47] op_sel_hi:[0,1]
	v_mov_b32_e32 v61, v47
	v_pk_add_f32 v[40:41], v[40:41], v[60:61]
	v_add_f32_e32 v43, v75, v63
	v_pk_add_f32 v[40:41], v[40:41], v[40:41] op_sel_hi:[0,1]
	v_mov_b32_e32 v63, v41
	v_pk_add_f32 v[40:41], v[42:43], v[62:63]
	v_add_f32_e32 v39, v74, v59
	v_pk_add_f32 v[40:41], v[40:41], v[40:41] op_sel_hi:[0,1]
	v_mov_b32_e32 v59, v41
	v_pk_add_f32 v[38:39], v[38:39], v[58:59]
	v_add_f32_e32 v37, v35, v55
	v_pk_add_f32 v[38:39], v[38:39], v[38:39] op_sel_hi:[0,1]
	v_mov_b32_e32 v57, v39
	v_pk_add_f32 v[36:37], v[36:37], v[56:57]
	v_add_f32_e32 v35, v44, v73
	v_pk_add_f32 v[36:37], v[36:37], v[36:37] op_sel_hi:[0,1]
	v_mov_b32_e32 v55, v37
	v_pk_add_f32 v[34:35], v[34:35], v[54:55]
	s_lshl_b64 s[4:5], s[8:9], 10
	v_add_f32_e32 v34, v34, v35
	v_add_f32_e32 v34, v72, v34
	v_mov_b32_e32 v35, v34
	s_nop 1
	v_permlane32_swap_b32_e32 v34, v35
	s_add_u32 s6, s54, s4
	v_add_f32_e32 v34, v34, v35
	s_addc_u32 s7, s55, s5
	v_div_scale_f32 v35, s[4:5], v34, v34, 1.0
	v_rcp_f32_e32 v36, v35
	s_lshl_b32 s4, s13, 1
	s_add_u32 s4, s6, s4
	s_addc_u32 s5, s7, 0
	v_fma_f32 v37, -v35, v36, 1.0
	v_fmac_f32_e32 v36, v37, v36
	v_div_scale_f32 v37, vcc, 1.0, v34, 1.0
	v_mul_f32_e32 v38, v37, v36
	v_fma_f32 v39, -v35, v38, v37
	v_fmac_f32_e32 v38, v39, v36
	v_fma_f32 v35, -v35, v38, v37
	v_div_fmas_f32 v35, v35, v36, v38
	v_div_fixup_f32 v34, v35, v34, 1.0
	v_mov_b32_e32 v35, v230
	v_mov_b32_e32 v37, v1
	v_lshlrev_b32_e32 v36, 10, v35
	v_and_b32_e32 v36, 0x7c00, v36
	v_lshrrev_b32_e32 v35, 2, v35
	v_lshl_add_u64 v[36:37], s[4:5], 0, v[36:37]
	v_and_b32_e32 v38, 8, v35
	v_mov_b32_e32 v39, v1
	v_lshl_add_u64 v[36:37], v[36:37], 0, v[38:39]
	v_lshl_add_u64 v[36:37], v[36:37], 0, v[38:39]
	v_pk_mul_f32 v[2:3], v[2:3], v[34:35] op_sel_hi:[1,0]
	v_pk_mul_f32 v[4:5], v[4:5], v[34:35] op_sel_hi:[1,0]
	v_pk_mul_f32 v[6:7], v[6:7], v[34:35] op_sel_hi:[1,0]
	v_pk_mul_f32 v[8:9], v[8:9], v[34:35] op_sel_hi:[1,0]
	v_pk_mul_f32 v[10:11], v[10:11], v[34:35] op_sel_hi:[1,0]
	v_pk_mul_f32 v[12:13], v[12:13], v[34:35] op_sel_hi:[1,0]
	v_pk_mul_f32 v[14:15], v[14:15], v[34:35] op_sel_hi:[1,0]
	v_pk_mul_f32 v[16:17], v[16:17], v[34:35] op_sel_hi:[1,0]
	v_pk_mul_f32 v[18:19], v[18:19], v[34:35] op_sel_hi:[1,0]
	v_pk_mul_f32 v[20:21], v[20:21], v[34:35] op_sel_hi:[1,0]
	v_pk_mul_f32 v[22:23], v[22:23], v[34:35] op_sel_hi:[1,0]
	v_pk_mul_f32 v[24:25], v[24:25], v[34:35] op_sel_hi:[1,0]
	v_pk_mul_f32 v[26:27], v[26:27], v[34:35] op_sel_hi:[1,0]
	v_pk_mul_f32 v[28:29], v[28:29], v[34:35] op_sel_hi:[1,0]
	v_pk_mul_f32 v[30:31], v[30:31], v[34:35] op_sel_hi:[1,0]
	v_pk_mul_f32 v[32:33], v[32:33], v[34:35] op_sel_hi:[1,0]
	v_cvt_pk_bf16_f32 v2, v2, v3
	v_cvt_pk_bf16_f32 v3, v4, v5
	v_cvt_pk_bf16_f32 v4, v6, v7
	v_cvt_pk_bf16_f32 v5, v8, v9
	v_cvt_pk_bf16_f32 v10, v10, v11
	v_cvt_pk_bf16_f32 v11, v12, v13
	v_cvt_pk_bf16_f32 v12, v14, v15
	v_cvt_pk_bf16_f32 v13, v16, v17
	v_cvt_pk_bf16_f32 v18, v18, v19
	v_cvt_pk_bf16_f32 v19, v20, v21
	v_cvt_pk_bf16_f32 v20, v22, v23
	v_cvt_pk_bf16_f32 v21, v24, v25
	v_cvt_pk_bf16_f32 v26, v26, v27
	v_cvt_pk_bf16_f32 v27, v28, v29
	v_cvt_pk_bf16_f32 v28, v30, v31
	v_cvt_pk_bf16_f32 v29, v32, v33
	s_nop 1
	v_permlane32_swap_b32_e32 v2, v4
	v_permlane32_swap_b32_e32 v3, v5
	flat_store_dwordx4 v[36:37], v[2:5]
	v_permlane32_swap_b32_e32 v10, v12
	v_permlane32_swap_b32_e32 v11, v13
	flat_store_dwordx4 v[36:37], v[10:13] offset:32
	v_permlane32_swap_b32_e32 v18, v20
	v_permlane32_swap_b32_e32 v19, v21
	flat_store_dwordx4 v[36:37], v[18:21] offset:64
	v_permlane32_swap_b32_e32 v26, v28
	v_permlane32_swap_b32_e32 v27, v29
	flat_store_dwordx4 v[36:37], v[26:29] offset:96
	s_add_i32 s12, s12, s94
	s_cmpk_gt_i32 s12, 0x1ff
	s_mov_b32 s13, s26
	s_cbranch_scc1 .LBB0_1027

; __device__ __forceinline__ unsigned pk2(float lo, float hi) { f32x2_t v = {lo, hi}; bf16x2_t b = __builtin_convertvector(v, bf16x2_t); return __builtin_bit_cast(unsigned, b); }
; template <bool SWA> ...
;     ...
;     int t = 0;
;     if (wv >= 4) __builtin_amdgcn_s_setprio(1);
;     for (; t < ntiles - 2; t += 2) { AT_STEP(t, sA0, sA1, sB0, sB1, true); AT_STEP(t + 1, sB0, sB1, sA0, sA1, true); }
;     AT_STEP(t, sA0, sA1, sB0, sB1, true);
;     AT_STEP(t + 1, sB0, sB1, sA0, sA1, false);
;     if (wv >= 4) __builtin_amdgcn_s_setprio(0);
;     ...
;     { auto rr = __builtin_amdgcn_permlane32_swap(__float_as_uint(lrun), __float_as_uint(lrun), false, false); lrun = __uint_as_float(rr[0]) + __uint_as_float(rr[1]); }
;     const float inv = 1.0f / lrun;
;     int tl2 = tid; asm volatile("" : "+v"(tl2));
;     bf16_t* Orow = Owave + (size_t)(tl2 & 31) * 512;
; #pragma unroll
;     for (int rq = 0; rq < 4; ++rq) {
;         u32x2 w; w.x = pk2(o0[4 * rq] * inv, o0[4 * rq + 1] * inv); w.y = pk2(o0[4 * rq + 2] * inv, o0[4 * rq + 3] * inv);
;         *(u32x2*)(Orow + 8 * rq + 4 * (tl2 & 32 ? 1 : 0)) = w;
;         w.x = pk2(o1[4 * rq] * inv, o1[4 * rq + 1] * inv); w.y = pk2(o1[4 * rq + 2] * inv, o1[4 * rq + 3] * inv);
;         *(u32x2*)(Orow + 32 + 8 * rq + 4 * (tl2 & 32 ? 1 : 0)) = w;
;     }
.LBB0_1026:
	v_add_f32_e32 v71, v67, v53
	v_mov_b32_e32 v53, v1
	v_pk_add_f32 v[46:47], v[70:71], v[52:53]
	v_add_f32_e32 v69, v65, v51
	v_pk_add_f32 v[46:47], v[46:47], v[46:47] op_sel_hi:[0,1]
	v_mov_b32_e32 v51, v47
	v_pk_add_f32 v[46:47], v[68:69], v[50:51]
	v_add_f32_e32 v67, v37, v61
	v_pk_add_f32 v[46:47], v[46:47], v[46:47] op_sel_hi:[0,1]
	v_mov_b32_e32 v65, v47
	v_pk_add_f32 v[46:47], v[66:67], v[64:65]
	v_add_f32_e32 v41, v39, v57
	v_pk_add_f32 v[46:47], v[46:47], v[46:47] op_sel_hi:[0,1]
	v_mov_b32_e32 v61, v47
	v_pk_add_f32 v[40:41], v[40:41], v[60:61]
	v_add_f32_e32 v43, v75, v63
	v_pk_add_f32 v[40:41], v[40:41], v[40:41] op_sel_hi:[0,1]
	v_mov_b32_e32 v63, v41
	v_pk_add_f32 v[40:41], v[42:43], v[62:63]
	v_add_f32_e32 v39, v74, v59
	v_pk_add_f32 v[40:41], v[40:41], v[40:41] op_sel_hi:[0,1]
	v_mov_b32_e32 v59, v41
	v_pk_add_f32 v[38:39], v[38:39], v[58:59]
	v_add_f32_e32 v37, v35, v55
	v_pk_add_f32 v[38:39], v[38:39], v[38:39] op_sel_hi:[0,1]
	v_mov_b32_e32 v57, v39
	v_pk_add_f32 v[36:37], v[36:37], v[56:57]
	v_add_f32_e32 v35, v44, v73
	v_pk_add_f32 v[36:37], v[36:37], v[36:37] op_sel_hi:[0,1]
	v_mov_b32_e32 v55, v37
	v_pk_add_f32 v[34:35], v[34:35], v[54:55]
	s_lshl_b64 s[4:5], s[8:9], 10
	v_add_f32_e32 v34, v34, v35
	v_add_f32_e32 v34, v72, v34
	v_mov_b32_e32 v35, v34
	s_nop 1
	v_permlane32_swap_b32_e32 v34, v35
	s_add_u32 s6, s54, s4
	v_add_f32_e32 v34, v34, v35
	s_addc_u32 s7, s55, s5
	v_div_scale_f32 v35, s[4:5], v34, v34, 1.0
	v_rcp_f32_e32 v36, v35
	s_lshl_b32 s4, s12, 1
	s_add_u32 s4, s6, s4
	s_addc_u32 s5, s7, 0
	v_fma_f32 v37, -v35, v36, 1.0
	v_fmac_f32_e32 v36, v37, v36
	v_div_scale_f32 v37, vcc, 1.0, v34, 1.0
	v_mul_f32_e32 v38, v37, v36
	v_fma_f32 v39, -v35, v38, v37
	v_fmac_f32_e32 v38, v39, v36
	v_fma_f32 v35, -v35, v38, v37
	v_div_fmas_f32 v35, v35, v36, v38
	v_div_fixup_f32 v34, v35, v34, 1.0
	v_mov_b32_e32 v35, v230
	v_mov_b32_e32 v37, v1
	v_lshlrev_b32_e32 v36, 10, v35
	v_and_b32_e32 v36, 0x7c00, v36
	v_lshrrev_b32_e32 v35, 2, v35
	v_lshl_add_u64 v[36:37], s[4:5], 0, v[36:37]
	v_and_b32_e32 v38, 8, v35
	v_mov_b32_e32 v39, v1
	v_lshl_add_u64 v[36:37], v[36:37], 0, v[38:39]
	v_lshl_add_u64 v[36:37], v[36:37], 0, v[38:39]
	v_pk_mul_f32 v[2:3], v[2:3], v[34:35] op_sel_hi:[1,0]
	v_pk_mul_f32 v[4:5], v[4:5], v[34:35] op_sel_hi:[1,0]
	v_pk_mul_f32 v[6:7], v[6:7], v[34:35] op_sel_hi:[1,0]
	v_pk_mul_f32 v[8:9], v[8:9], v[34:35] op_sel_hi:[1,0]
	v_pk_mul_f32 v[10:11], v[10:11], v[34:35] op_sel_hi:[1,0]
	v_pk_mul_f32 v[12:13], v[12:13], v[34:35] op_sel_hi:[1,0]
	v_pk_mul_f32 v[14:15], v[14:15], v[34:35] op_sel_hi:[1,0]
	v_pk_mul_f32 v[16:17], v[16:17], v[34:35] op_sel_hi:[1,0]
	v_pk_mul_f32 v[18:19], v[18:19], v[34:35] op_sel_hi:[1,0]
	v_pk_mul_f32 v[20:21], v[20:21], v[34:35] op_sel_hi:[1,0]
	v_pk_mul_f32 v[22:23], v[22:23], v[34:35] op_sel_hi:[1,0]
	v_pk_mul_f32 v[24:25], v[24:25], v[34:35] op_sel_hi:[1,0]
	v_pk_mul_f32 v[26:27], v[26:27], v[34:35] op_sel_hi:[1,0]
	v_pk_mul_f32 v[28:29], v[28:29], v[34:35] op_sel_hi:[1,0]
	v_pk_mul_f32 v[30:31], v[30:31], v[34:35] op_sel_hi:[1,0]
	v_pk_mul_f32 v[32:33], v[32:33], v[34:35] op_sel_hi:[1,0]
	v_cvt_pk_bf16_f32 v2, v2, v3
	v_cvt_pk_bf16_f32 v3, v4, v5
	v_cvt_pk_bf16_f32 v4, v6, v7
	v_cvt_pk_bf16_f32 v5, v8, v9
	v_cvt_pk_bf16_f32 v10, v10, v11
	v_cvt_pk_bf16_f32 v11, v12, v13
	v_cvt_pk_bf16_f32 v12, v14, v15
	v_cvt_pk_bf16_f32 v13, v16, v17
	v_cvt_pk_bf16_f32 v18, v18, v19
	v_cvt_pk_bf16_f32 v19, v20, v21
	v_cvt_pk_bf16_f32 v20, v22, v23
	v_cvt_pk_bf16_f32 v21, v24, v25
	v_cvt_pk_bf16_f32 v26, v26, v27
	v_cvt_pk_bf16_f32 v27, v28, v29
	v_cvt_pk_bf16_f32 v28, v30, v31
	v_cvt_pk_bf16_f32 v29, v32, v33
	s_nop 1
	v_permlane32_swap_b32_e32 v2, v4
	v_permlane32_swap_b32_e32 v3, v5
	flat_store_dwordx4 v[36:37], v[2:5]
	v_permlane32_swap_b32_e32 v10, v12
	v_permlane32_swap_b32_e32 v11, v13
	flat_store_dwordx4 v[36:37], v[10:13] offset:32
	v_permlane32_swap_b32_e32 v18, v20
	v_permlane32_swap_b32_e32 v19, v21
	flat_store_dwordx4 v[36:37], v[18:21] offset:64
	v_permlane32_swap_b32_e32 v26, v28
	v_permlane32_swap_b32_e32 v27, v29
	flat_store_dwordx4 v[36:37], v[26:29] offset:96
	s_add_i32 s13, s13, s94
	s_cmpk_gt_i32 s13, 0x1ff
	s_cbranch_scc1 .LBB0_1052

; __device__ __forceinline__ unsigned pk2(float lo, float hi) { f32x2_t v = {lo, hi}; bf16x2_t b = __builtin_convertvector(v, bf16x2_t); return __builtin_bit_cast(unsigned, b); }
; template <bool SWA> ...
;     ...
;     int t = 0;
;     if (wv >= 4) __builtin_amdgcn_s_setprio(1);
;     for (; t < ntiles - 2; t += 2) { AT_STEP(t, sA0, sA1, sB0, sB1, true); AT_STEP(t + 1, sB0, sB1, sA0, sA1, true); }
;     AT_STEP(t, sA0, sA1, sB0, sB1, true);
;     AT_STEP(t + 1, sB0, sB1, sA0, sA1, false);
;     if (wv >= 4) __builtin_amdgcn_s_setprio(0);
;     ...
;     { auto rr = __builtin_amdgcn_permlane32_swap(__float_as_uint(lrun), __float_as_uint(lrun), false, false); lrun = __uint_as_float(rr[0]) + __uint_as_float(rr[1]); }
;     const float inv = 1.0f / lrun;
;     int tl2 = tid; asm volatile("" : "+v"(tl2));
;     bf16_t* Orow = Owave + (size_t)(tl2 & 31) * 512;
; #pragma unroll
;     for (int rq = 0; rq < 4; ++rq) {
;         u32x2 w; w.x = pk2(o0[4 * rq] * inv, o0[4 * rq + 1] * inv); w.y = pk2(o0[4 * rq + 2] * inv, o0[4 * rq + 3] * inv);
;         *(u32x2*)(Orow + 8 * rq + 4 * (tl2 & 32 ? 1 : 0)) = w;
;         w.x = pk2(o1[4 * rq] * inv, o1[4 * rq + 1] * inv); w.y = pk2(o1[4 * rq + 2] * inv, o1[4 * rq + 3] * inv);
;         *(u32x2*)(Orow + 32 + 8 * rq + 4 * (tl2 & 32 ? 1 : 0)) = w;
;     }
.LBB0_1056:
	v_add_f32_e32 v63, v63, v71
	v_pk_add_f32 v[44:45], v[62:63], v[0:1]
	v_add_f32_e32 v59, v59, v49
	v_pk_add_f32 v[44:45], v[44:45], v[44:45] op_sel_hi:[0,1]
	v_mov_b32_e32 v49, v45
	v_pk_add_f32 v[44:45], v[58:59], v[48:49]
	v_add_f32_e32 v39, v61, v65
	v_pk_add_f32 v[44:45], v[44:45], v[44:45] op_sel_hi:[0,1]
	v_mov_b32_e32 v69, v45
	v_pk_add_f32 v[38:39], v[38:39], v[68:69]
	v_add_f32_e32 v51, v73, v67
	v_pk_add_f32 v[38:39], v[38:39], v[38:39] op_sel_hi:[0,1]
	v_mov_b32_e32 v65, v39
	v_pk_add_f32 v[38:39], v[50:51], v[64:65]
	v_add_f32_e32 v61, v74, v72
	v_pk_add_f32 v[38:39], v[38:39], v[38:39] op_sel_hi:[0,1]
	v_mov_b32_e32 v67, v39
	v_pk_add_f32 v[38:39], v[60:61], v[66:67]
	v_add_f32_e32 v41, v41, v57
	v_pk_add_f32 v[38:39], v[38:39], v[38:39] op_sel_hi:[0,1]
	v_mov_b32_e32 v57, v39
	v_pk_add_f32 v[38:39], v[40:41], v[56:57]
	v_add_f32_e32 v35, v35, v53
	v_pk_add_f32 v[38:39], v[38:39], v[38:39] op_sel_hi:[0,1]
	v_mov_b32_e32 v53, v39
	v_pk_add_f32 v[34:35], v[34:35], v[52:53]
	v_add_f32_e32 v37, v37, v55
	v_pk_add_f32 v[34:35], v[34:35], v[34:35] op_sel_hi:[0,1]
	v_mov_b32_e32 v55, v35
	v_pk_add_f32 v[34:35], v[36:37], v[54:55]
	v_lshl_add_u64 v[42:43], s[26:27], 1, v[176:177]
	v_add_f32_e32 v0, v34, v35
	v_add_f32_e32 v0, v70, v0
	v_mov_b32_e32 v34, v0
	s_nop 1
	v_permlane32_swap_b32_e32 v0, v34
	v_add_f32_e32 v0, v0, v34
	v_div_scale_f32 v34, s[20:21], v0, v0, 1.0
	v_rcp_f32_e32 v35, v34
	s_add_u32 s16, s16, 1
	s_addc_u32 s17, s17, 0
	s_cmp_eq_u32 s16, 4
	v_fma_f32 v36, -v34, v35, 1.0
	v_fmac_f32_e32 v35, v36, v35
	v_div_scale_f32 v36, vcc, 1.0, v0, 1.0
	v_mul_f32_e32 v37, v36, v35
	v_fma_f32 v38, -v34, v37, v36
	v_fmac_f32_e32 v37, v38, v35
	v_fma_f32 v34, -v34, v37, v36
	v_div_fmas_f32 v34, v34, v35, v37
	v_mov_b32_e32 v35, v230
	v_div_fixup_f32 v34, v34, v0, 1.0
	s_nop 0
	v_lshlrev_b32_e32 v0, 10, v35
	v_and_b32_e32 v0, 0x7c00, v0
	v_lshl_add_u64 v[36:37], v[42:43], 0, v[0:1]
	v_lshrrev_b32_e32 v0, 2, v35
	v_and_b32_e32 v0, 8, v0
	v_lshl_add_u64 v[36:37], v[36:37], 0, v[0:1]
	v_lshl_add_u64 v[36:37], v[36:37], 0, v[0:1]
	v_pk_mul_f32 v[2:3], v[2:3], v[34:35] op_sel_hi:[1,0]
	v_pk_mul_f32 v[4:5], v[4:5], v[34:35] op_sel_hi:[1,0]
	v_pk_mul_f32 v[6:7], v[6:7], v[34:35] op_sel_hi:[1,0]
	v_pk_mul_f32 v[8:9], v[8:9], v[34:35] op_sel_hi:[1,0]
	v_pk_mul_f32 v[10:11], v[10:11], v[34:35] op_sel_hi:[1,0]
	v_pk_mul_f32 v[12:13], v[12:13], v[34:35] op_sel_hi:[1,0]
	v_pk_mul_f32 v[14:15], v[14:15], v[34:35] op_sel_hi:[1,0]
	v_pk_mul_f32 v[16:17], v[16:17], v[34:35] op_sel_hi:[1,0]
	v_pk_mul_f32 v[18:19], v[18:19], v[34:35] op_sel_hi:[1,0]
	v_pk_mul_f32 v[20:21], v[20:21], v[34:35] op_sel_hi:[1,0]
	v_pk_mul_f32 v[22:23], v[22:23], v[34:35] op_sel_hi:[1,0]
	v_pk_mul_f32 v[24:25], v[24:25], v[34:35] op_sel_hi:[1,0]
	v_pk_mul_f32 v[26:27], v[26:27], v[34:35] op_sel_hi:[1,0]
	v_pk_mul_f32 v[28:29], v[28:29], v[34:35] op_sel_hi:[1,0]
	v_pk_mul_f32 v[30:31], v[30:31], v[34:35] op_sel_hi:[1,0]
	v_pk_mul_f32 v[32:33], v[32:33], v[34:35] op_sel_hi:[1,0]
	v_cvt_pk_bf16_f32 v2, v2, v3
	v_cvt_pk_bf16_f32 v3, v4, v5
	v_cvt_pk_bf16_f32 v4, v6, v7
	v_cvt_pk_bf16_f32 v5, v8, v9
	v_cvt_pk_bf16_f32 v10, v10, v11
	v_cvt_pk_bf16_f32 v11, v12, v13
	v_cvt_pk_bf16_f32 v12, v14, v15
	v_cvt_pk_bf16_f32 v13, v16, v17
	v_cvt_pk_bf16_f32 v18, v18, v19
	v_cvt_pk_bf16_f32 v19, v20, v21
	v_cvt_pk_bf16_f32 v20, v22, v23
	v_cvt_pk_bf16_f32 v21, v24, v25
	v_cvt_pk_bf16_f32 v26, v26, v27
	v_cvt_pk_bf16_f32 v27, v28, v29
	v_cvt_pk_bf16_f32 v28, v30, v31
	v_cvt_pk_bf16_f32 v29, v32, v33
	s_nop 1
	v_permlane32_swap_b32_e32 v2, v4
	v_permlane32_swap_b32_e32 v3, v5
	flat_store_dwordx4 v[36:37], v[2:5] offset:64
	v_permlane32_swap_b32_e32 v10, v12
	v_permlane32_swap_b32_e32 v11, v13
	flat_store_dwordx4 v[36:37], v[10:13] offset:96
	v_permlane32_swap_b32_e32 v18, v20
	v_permlane32_swap_b32_e32 v19, v21
	flat_store_dwordx4 v[36:37], v[18:21]
	v_permlane32_swap_b32_e32 v26, v28
	v_permlane32_swap_b32_e32 v27, v29
	flat_store_dwordx4 v[36:37], v[26:29] offset:32
	s_cbranch_scc1 .LBB0_1054
